# phase 3 gMLP items: gmlp_norm_g/b float4 lookups read from LDS tables staged once per workgroup instead of 16 dependent global round trips per item
# speedup vs baseline: 1.0042x; 1.0042x over previous
.LBB0_330:
	s_or_b64 exec, exec, s[0:1]
	s_waitcnt lgkmcnt(0)
	v_mov_b32_e32 v0, v254
	s_cmpk_gt_i32 s2, 0x7ff
	s_barrier
	s_cbranch_scc1 .LBB0_409
	v_bfe_u32 v6, v0, 5, 1
	v_ashrrev_i32_e32 v187, 5, v0
	v_lshlrev_b32_e32 v9, 9, v0
	v_lshlrev_b32_e32 v18, 3, v6
	s_movk_i32 s6, 0xff00
	v_lshlrev_b32_e32 v23, 2, v187
	v_bfe_u32 v1, v0, 2, 2
	v_lshrrev_b32_e32 v2, 3, v0
	v_bfe_u32 v4, v0, 1, 1
	v_and_b32_e32 v7, 31, v0
	v_bfe_u32 v149, v0, 6, 2
	v_ashrrev_i32_e32 v8, 8, v0
	v_and_b32_e32 v9, 0x2000, v9
	v_and_b32_e32 v10, 15, v0
	v_bfe_u32 v11, v187, 2, 2
	v_ashrrev_i32_e32 v12, 2, v0
	v_lshlrev_b32_e32 v13, 7, v0
	v_lshlrev_b32_e32 v14, 12, v0
	v_lshlrev_b32_e32 v15, 3, v0
	v_and_b32_e32 v17, 12, v0
	v_and_or_b32 v19, v0, s6, v18
	v_lshlrev_b32_e32 v0, 9, v187
	v_and_b32_e32 v23, 12, v23
	v_add_u32_e32 v9, 0, v9
	v_and_b32_e32 v21, 0xffffc000, v0
	v_lshlrev_b32_e32 v22, 8, v187
	v_bitop3_b32 v23, v23, v10, v11 bitop3:0x36
	v_add_u32_e32 v21, v9, v21
	v_and_b32_e32 v22, 0x1f00, v22
	v_lshlrev_b32_e32 v23, 4, v23
	v_add3_u32 v189, v21, v23, v22
	v_add_u32_e32 v21, 16, v187
	v_lshlrev_b32_e32 v24, 9, v21
	v_and_b32_e32 v25, 31, v21
	v_lshlrev_b32_e32 v21, 2, v21
	v_and_b32_e32 v21, 12, v21
	v_and_b32_e32 v24, 0xffffc000, v24
	v_bitop3_b32 v21, v21, v10, v11 bitop3:0x36
	v_add_u32_e32 v24, v9, v24
	v_lshlrev_b32_e32 v25, 8, v25
	v_lshlrev_b32_e32 v21, 4, v21
	v_add3_u32 v191, v24, v21, v25
	v_add_u32_e32 v21, 0x4000, v0
	v_and_b32_e32 v21, 0xffffc000, v21
	v_add_u32_e32 v21, v9, v21
	v_add3_u32 v192, v21, v23, v22
	v_add_u32_e32 v21, 48, v187
	v_lshlrev_b32_e32 v24, 9, v21
	v_and_b32_e32 v25, 31, v21
	v_lshlrev_b32_e32 v21, 2, v21
	v_and_b32_e32 v21, 12, v21
	v_and_b32_e32 v24, 0xffffc000, v24
	v_bitop3_b32 v21, v21, v10, v11 bitop3:0x36
	v_add_u32_e32 v24, v9, v24
	v_lshlrev_b32_e32 v25, 8, v25
	v_lshlrev_b32_e32 v21, 4, v21
	v_add3_u32 v193, v24, v21, v25
	v_add_u32_e32 v21, 0x8000, v0
	v_and_b32_e32 v21, 0xffffc000, v21
	v_add_u32_e32 v21, v9, v21
	v_add3_u32 v194, v21, v23, v22
	v_add_u32_e32 v21, 0x50, v187
	v_lshlrev_b32_e32 v24, 9, v21
	v_and_b32_e32 v25, 31, v21
	v_lshlrev_b32_e32 v21, 2, v21
	v_add_u32_e32 v0, 0xc000, v0
	v_and_b32_e32 v21, 12, v21
	v_and_b32_e32 v0, 0xffffc000, v0
	v_and_b32_e32 v24, 0xffffc000, v24
	v_bitop3_b32 v21, v21, v10, v11 bitop3:0x36
	v_add_u32_e32 v0, v9, v0
	v_add_u32_e32 v24, v9, v24
	v_lshlrev_b32_e32 v25, 8, v25
	v_lshlrev_b32_e32 v21, 4, v21
	v_add3_u32 v196, v0, v23, v22
	v_add_u32_e32 v0, 0x70, v187
	v_add3_u32 v195, v24, v21, v25
	v_lshlrev_b32_e32 v21, 9, v0
	v_and_b32_e32 v21, 0xffffc000, v21
	v_add_u32_e32 v9, v9, v21
	v_and_b32_e32 v21, 31, v0
	v_lshlrev_b32_e32 v0, 2, v0
	v_and_b32_e32 v0, 12, v0
	v_bitop3_b32 v0, v0, v10, v11 bitop3:0x36
	v_and_b32_e32 v15, 8, v15
	v_lshlrev_b32_e32 v16, 8, v12
	v_bfe_u32 v12, v12, 2, 2
	v_lshlrev_b32_e32 v21, 8, v21
	v_lshlrev_b32_e32 v0, 4, v0
	v_add3_u32 v197, v9, v0, v21
	v_bitop3_b32 v0, v17, v15, v12 bitop3:0x36
	v_lshlrev_b32_e32 v9, 4, v0
	v_or_b32_e32 v0, 1, v15
	v_bitop3_b32 v0, v17, v0, v12 bitop3:0x36
	v_lshlrev_b32_e32 v10, 4, v0
	v_or_b32_e32 v0, 2, v15
	v_bitop3_b32 v0, v17, v0, v12 bitop3:0x36
	v_lshlrev_b32_e32 v11, 4, v0
	v_or_b32_e32 v0, 3, v15
	v_bitop3_b32 v0, v17, v0, v12 bitop3:0x36
	v_lshlrev_b32_e32 v21, 4, v0
	v_or_b32_e32 v0, 4, v15
	v_and_b32_e32 v13, 0xffffc000, v13
	v_bitop3_b32 v0, v17, v0, v12 bitop3:0x36
	v_add_u32_e32 v13, 0, v13
	v_and_b32_e32 v14, 0x2000, v14
	v_and_b32_e32 v16, 0x1f00, v16
	v_lshlrev_b32_e32 v22, 4, v0
	v_or_b32_e32 v0, 5, v15
	v_add3_u32 v13, v13, v14, v16
	v_lshlrev_b32_e32 v14, 13, v8
	v_lshlrev_b32_e32 v16, 11, v6
	v_bitop3_b32 v0, v17, v0, v12 bitop3:0x36
	v_add3_u32 v14, 0, v14, v16
	v_lshlrev_b32_e32 v16, 8, v1
	v_lshlrev_b32_e32 v23, 4, v0
	v_or_b32_e32 v0, 6, v15
	v_and_b32_e32 v3, 2, v2
	v_add3_u32 v14, v14, v16, v15
	v_lshlrev_b32_e32 v16, 1, v6
	v_bitop3_b32 v0, v17, v0, v12 bitop3:0x36
	s_add_u32 s8, s28, 0x80000
	v_or_b32_e32 v5, v3, v4
	v_lshlrev_b32_e32 v148, 3, v7
	v_bitop3_b32 v3, v3, v16, v4 bitop3:0x36
	v_lshlrev_b32_e32 v4, 7, v8
	v_lshlrev_b32_e32 v24, 4, v0
	v_or_b32_e32 v0, 7, v15
	s_addc_u32 s9, s29, 0
	v_lshl_or_b32 v2, v149, 8, v148
	v_mov_b32_e32 v151, 0
	v_lshlrev_b32_e32 v150, 4, v7
	v_bitop3_b32 v16, v16, v5, 1 bitop3:0x36
	v_ashrrev_i32_e32 v5, 31, v4
	s_add_i32 s0, 0, 0x10000
	v_bitop3_b32 v0, v17, v0, v12 bitop3:0x36
	v_lshl_add_u64 v[152:153], s[70:71], 0, v[150:151]
	v_add_u32_e32 v20, s0, v150
	v_lshlrev_b32_e32 v12, 4, v0
	v_lshlrev_b32_e32 v200, 6, v1
	v_lshlrev_b32_e32 v150, 2, v2
	v_lshlrev_b64 v[0:1], 2, v[4:5]
	v_lshl_or_b32 v188, v149, 5, v7
	s_movk_i32 s1, 0x210
	v_mov_b32_e32 v7, s0
	v_lshl_add_u64 v[154:155], s[62:63], 0, v[150:151]
	v_lshl_add_u64 v[156:157], s[64:65], 0, v[150:151]
	v_lshl_add_u64 v[4:5], s[52:53], 0, v[0:1]
	v_lshlrev_b32_e32 v150, 4, v6
	v_lshl_add_u64 v[0:1], s[54:55], 0, v[0:1]
	v_mad_u32_u24 v7, v188, s1, v7
	v_lshl_add_u32 v198, v3, 4, v14
	v_mul_lo_u32 v3, v187, s1
	v_lshl_add_u64 v[158:159], v[4:5], 0, v[150:151]
	v_lshl_add_u64 v[160:161], v[0:1], 0, v[150:151]
	v_subrev_u32_e32 v246, s52, v158
	v_add_u32_e32 v247, 0x20c00, v246
	v_add_u32_e32 v246, 0x20800, v246
	s_mov_b64 s[98:99], exec
	v_cmp_gt_u32_e32 vcc, 64, v254
	s_and_b64 exec, exec, vcc
	v_lshlrev_b32_e32 v248, 4, v254
	global_load_dwordx4 v[250:253], v248, s[52:53]
	v_add_u32_e32 v249, 0x20800, v248
	s_waitcnt vmcnt(0)
	ds_write_b128 v249, v[250:253]
	global_load_dwordx4 v[250:253], v248, s[54:55]
	v_add_u32_e32 v249, 0x20c00, v248
	s_waitcnt vmcnt(0)
	ds_write_b128 v249, v[250:253]
	s_waitcnt lgkmcnt(0)
	s_mov_b64 exec, s[98:99]
	v_lshl_or_b32 v0, v149, 4, v6
	v_lshlrev_b32_e32 v150, 1, v2
	s_mov_b32 s13, 0
	v_cmp_lt_u32_e64 s[4:5], 1, v149
	s_mov_b32 s3, 0x10000
	s_mov_b32 s51, 0x8000
	s_mov_b32 s66, 0xc000
	v_lshl_add_u32 v199, v16, 4, v14
	v_xor_b32_e32 v201, 64, v200
	v_xor_b32_e32 v202, 0x80, v200
	v_xor_b32_e32 v203, 0xc0, v200
	v_lshl_add_u64 v[162:163], s[18:19], 0, v[150:151]
	v_lshl_or_b32 v204, v8, 4, v18
	s_lshl_b32 s53, s2, 5
	s_lshl_b32 s55, s30, 5
	s_movk_i32 s62, 0x2800
	v_lshlrev_b32_e32 v164, 1, v2
	s_mov_b64 s[24:25], 0x1800
	s_mov_b32 s63, 0xf000
	s_mov_b32 s64, 0x11000
	s_movk_i32 s65, 0x3000
	s_mov_b32 s67, 0xd000
	s_mov_b32 s70, 0x12000
	s_mov_b32 s50, 0x3e000000
	s_mov_b32 s52, 0x3e800000
	v_lshlrev_b32_e32 v205, 9, v0
	s_movk_i32 s71, 0x1000
	s_mov_b32 s72, 0x28000
	s_mov_b32 s73, 0x50000
	s_mov_b32 s74, 0x78000
	s_mov_b32 s75, 0xa0000
	s_mov_b32 s76, 0xc8000
	s_mov_b32 s77, 0xf0000
	s_mov_b32 s78, 0x118000
	v_add_u32_e32 v206, v13, v9
	v_add_u32_e32 v207, v13, v10
	v_add_u32_e32 v208, v13, v11
	v_add_u32_e32 v209, v13, v24
	v_add_u32_e32 v210, v13, v21
	v_add_u32_e32 v211, v13, v22
	v_add_u32_e32 v212, v13, v23
	v_add_u32_e32 v213, v13, v12
	s_mov_b32 s54, 0x3b800000
	s_mov_b32 s79, 0x800000
	s_mov_b32 s80, 0x29000
	s_mov_b32 s81, 0x51000
	s_mov_b32 s82, 0x79000
	s_mov_b32 s83, 0xa1000
	s_mov_b32 s84, 0xc9000
	s_mov_b32 s85, 0xf1000
	s_mov_b32 s86, 0x119000
	v_add_u32_e32 v214, v7, v19
	v_add_u32_e32 v215, v20, v3
	s_mov_b32 s87, 0x20000
	s_mov_b32 s88, 0x30000
	s_mov_b32 s89, 0x40000
	s_mov_b32 s90, 0x60000
	v_mbcnt_hi_u32_b32 v216, -1, v186
	s_mov_b32 s91, s2
	s_branch .LBB0_334
.LBB0_332:
	s_or_b64 exec, exec, s[0:1]
	s_lshl_b32 s0, s6, 7
	s_waitcnt vmcnt(16)
	v_or_b32_e32 v128, s0, v188
	v_lshlrev_b32_e32 v128, 2, v128
	global_load_dword v128, v128, s[8:9]
	s_nop 0
	ds_read_b128 v[130:133], v246
	ds_read_b128 v[134:137], v247
	v_ashrrev_i32_e32 v167, 31, v166
	s_lshl_b32 s12, s7, 1
	s_waitcnt vmcnt(0) lgkmcnt(0)
	v_pk_mul_f32 v[134:135], v[128:129], v[134:135] op_sel_hi:[0,1]
	v_pk_fma_f32 v[48:49], v[48:49], v[130:131], v[134:135]
	s_nop 0
	v_cvt_pk_f16_f32 v134, v48, v49
	v_pk_mul_f32 v[48:49], v[128:129], v[136:137] op_sel_hi:[0,1]
	v_pk_fma_f32 v[48:49], v[50:51], v[132:133], v[48:49]
	s_nop 0
	v_cvt_pk_f16_f32 v135, v48, v49
	ds_read_b128 v[48:51], v246 offset:32
	ds_read_b128 v[130:133], v247 offset:32
	s_waitcnt lgkmcnt(0)
	v_pk_mul_f32 v[130:131], v[128:129], v[130:131] op_sel_hi:[0,1]
	v_pk_fma_f32 v[48:49], v[52:53], v[48:49], v[130:131]
	v_pk_mul_f32 v[52:53], v[128:129], v[132:133] op_sel_hi:[0,1]
	v_pk_fma_f32 v[50:51], v[54:55], v[50:51], v[52:53]
	v_cvt_pk_f16_f32 v48, v48, v49
	v_cvt_pk_f16_f32 v49, v50, v51
	ds_write2_b64 v214, v[134:135], v[48:49] offset1:2
	ds_read_b128 v[48:51], v246 offset:64
	ds_read_b128 v[52:55], v247 offset:64
	s_waitcnt lgkmcnt(0)
	v_pk_mul_f32 v[52:53], v[128:129], v[52:53] op_sel_hi:[0,1]
	v_pk_fma_f32 v[48:49], v[56:57], v[48:49], v[52:53]
	s_nop 0
	v_cvt_pk_f16_f32 v56, v48, v49
	v_pk_mul_f32 v[48:49], v[128:129], v[54:55] op_sel_hi:[0,1]
	v_pk_fma_f32 v[48:49], v[58:59], v[50:51], v[48:49]
	s_nop 0
	v_cvt_pk_f16_f32 v57, v48, v49
	ds_read_b128 v[48:51], v246 offset:96
	ds_read_b128 v[52:55], v247 offset:96
	s_waitcnt lgkmcnt(0)
	v_pk_mul_f32 v[52:53], v[128:129], v[52:53] op_sel_hi:[0,1]
	v_pk_fma_f32 v[48:49], v[60:61], v[48:49], v[52:53]
	v_pk_mul_f32 v[52:53], v[128:129], v[54:55] op_sel_hi:[0,1]
	v_pk_fma_f32 v[50:51], v[62:63], v[50:51], v[52:53]
	v_cvt_pk_f16_f32 v48, v48, v49
	v_cvt_pk_f16_f32 v49, v50, v51
	ds_write2_b64 v214, v[56:57], v[48:49] offset0:4 offset1:6
	ds_read_b128 v[48:51], v246 offset:128
	ds_read_b128 v[52:55], v247 offset:128
	s_waitcnt lgkmcnt(0)
	v_pk_mul_f32 v[52:53], v[128:129], v[52:53] op_sel_hi:[0,1]
	v_pk_fma_f32 v[32:33], v[32:33], v[48:49], v[52:53]
	s_nop 0
	v_cvt_pk_f16_f32 v52, v32, v33
	v_pk_mul_f32 v[32:33], v[128:129], v[54:55] op_sel_hi:[0,1]
	v_pk_fma_f32 v[32:33], v[34:35], v[50:51], v[32:33]
	s_nop 0
	v_cvt_pk_f16_f32 v53, v32, v33
	ds_read_b128 v[32:35], v246 offset:160
	ds_read_b128 v[48:51], v247 offset:160
	s_waitcnt lgkmcnt(0)
	v_pk_mul_f32 v[48:49], v[128:129], v[48:49] op_sel_hi:[0,1]
	v_pk_fma_f32 v[32:33], v[36:37], v[32:33], v[48:49]
	v_pk_mul_f32 v[36:37], v[128:129], v[50:51] op_sel_hi:[0,1]
	v_pk_fma_f32 v[34:35], v[38:39], v[34:35], v[36:37]
	v_cvt_pk_f16_f32 v32, v32, v33
	v_cvt_pk_f16_f32 v33, v34, v35
	ds_write2_b64 v214, v[52:53], v[32:33] offset0:8 offset1:10
	ds_read_b128 v[32:35], v246 offset:192
	ds_read_b128 v[36:39], v247 offset:192
	s_waitcnt lgkmcnt(0)
	v_pk_mul_f32 v[36:37], v[128:129], v[36:37] op_sel_hi:[0,1]
	v_pk_fma_f32 v[32:33], v[40:41], v[32:33], v[36:37]
	s_nop 0
	v_cvt_pk_f16_f32 v40, v32, v33
	v_pk_mul_f32 v[32:33], v[128:129], v[38:39] op_sel_hi:[0,1]
	v_pk_fma_f32 v[32:33], v[42:43], v[34:35], v[32:33]
	s_nop 0
	v_cvt_pk_f16_f32 v41, v32, v33
	ds_read_b128 v[32:35], v246 offset:224
	ds_read_b128 v[36:39], v247 offset:224
	s_waitcnt lgkmcnt(0)
	v_pk_mul_f32 v[36:37], v[128:129], v[36:37] op_sel_hi:[0,1]
	v_pk_fma_f32 v[32:33], v[44:45], v[32:33], v[36:37]
	v_pk_mul_f32 v[36:37], v[128:129], v[38:39] op_sel_hi:[0,1]
	v_pk_fma_f32 v[34:35], v[46:47], v[34:35], v[36:37]
	v_cvt_pk_f16_f32 v32, v32, v33
	v_cvt_pk_f16_f32 v33, v34, v35
	ds_write2_b64 v214, v[40:41], v[32:33] offset0:12 offset1:14
	ds_read_b128 v[32:35], v246 offset:256
	ds_read_b128 v[36:39], v247 offset:256
	s_waitcnt lgkmcnt(0)
	v_pk_mul_f32 v[36:37], v[128:129], v[36:37] op_sel_hi:[0,1]
	v_pk_fma_f32 v[16:17], v[16:17], v[32:33], v[36:37]
	s_nop 0
	v_cvt_pk_f16_f32 v36, v16, v17
	v_pk_mul_f32 v[16:17], v[128:129], v[38:39] op_sel_hi:[0,1]
	v_pk_fma_f32 v[16:17], v[18:19], v[34:35], v[16:17]
	s_nop 0
	v_cvt_pk_f16_f32 v37, v16, v17
	ds_read_b128 v[16:19], v246 offset:288
	ds_read_b128 v[32:35], v247 offset:288
	s_waitcnt lgkmcnt(0)
	v_pk_mul_f32 v[32:33], v[128:129], v[32:33] op_sel_hi:[0,1]
	v_pk_fma_f32 v[16:17], v[20:21], v[16:17], v[32:33]
	v_pk_mul_f32 v[20:21], v[128:129], v[34:35] op_sel_hi:[0,1]
	v_pk_fma_f32 v[18:19], v[22:23], v[18:19], v[20:21]
	v_cvt_pk_f16_f32 v16, v16, v17
	v_cvt_pk_f16_f32 v17, v18, v19
	ds_write2_b64 v214, v[36:37], v[16:17] offset0:16 offset1:18
	ds_read_b128 v[16:19], v246 offset:320
	ds_read_b128 v[20:23], v247 offset:320
	s_waitcnt lgkmcnt(0)
	v_pk_mul_f32 v[20:21], v[128:129], v[20:21] op_sel_hi:[0,1]
	v_pk_fma_f32 v[16:17], v[24:25], v[16:17], v[20:21]
	s_nop 0
	v_cvt_pk_f16_f32 v24, v16, v17
	v_pk_mul_f32 v[16:17], v[128:129], v[22:23] op_sel_hi:[0,1]
	v_pk_fma_f32 v[16:17], v[26:27], v[18:19], v[16:17]
	s_nop 0
	v_cvt_pk_f16_f32 v25, v16, v17
	ds_read_b128 v[16:19], v246 offset:352
	ds_read_b128 v[20:23], v247 offset:352
	s_waitcnt lgkmcnt(0)
	v_pk_mul_f32 v[20:21], v[128:129], v[20:21] op_sel_hi:[0,1]
	v_pk_fma_f32 v[16:17], v[28:29], v[16:17], v[20:21]
	v_pk_mul_f32 v[20:21], v[128:129], v[22:23] op_sel_hi:[0,1]
	v_pk_fma_f32 v[18:19], v[30:31], v[18:19], v[20:21]
	v_cvt_pk_f16_f32 v16, v16, v17
	v_cvt_pk_f16_f32 v17, v18, v19
	ds_write2_b64 v214, v[24:25], v[16:17] offset0:20 offset1:22
	ds_read_b128 v[16:19], v246 offset:384
	ds_read_b128 v[20:23], v247 offset:384
	s_waitcnt lgkmcnt(0)
	v_pk_mul_f32 v[20:21], v[128:129], v[20:21] op_sel_hi:[0,1]
	v_pk_fma_f32 v[0:1], v[0:1], v[16:17], v[20:21]
	s_nop 0
	v_cvt_pk_f16_f32 v20, v0, v1
	v_pk_mul_f32 v[0:1], v[128:129], v[22:23] op_sel_hi:[0,1]
	v_pk_fma_f32 v[0:1], v[2:3], v[18:19], v[0:1]
	s_nop 0
	v_cvt_pk_f16_f32 v21, v0, v1
	ds_read_b128 v[0:3], v246 offset:416
	ds_read_b128 v[16:19], v247 offset:416
	s_waitcnt lgkmcnt(0)
	v_pk_mul_f32 v[16:17], v[128:129], v[16:17] op_sel_hi:[0,1]
	v_pk_fma_f32 v[0:1], v[4:5], v[0:1], v[16:17]
	v_pk_mul_f32 v[4:5], v[128:129], v[18:19] op_sel_hi:[0,1]
	v_pk_fma_f32 v[2:3], v[6:7], v[2:3], v[4:5]
	v_cvt_pk_f16_f32 v0, v0, v1
	v_cvt_pk_f16_f32 v1, v2, v3
	ds_write2_b64 v214, v[20:21], v[0:1] offset0:24 offset1:26
	ds_read_b128 v[0:3], v246 offset:448
	ds_read_b128 v[4:7], v247 offset:448
	s_waitcnt lgkmcnt(0)
	v_pk_mul_f32 v[4:5], v[128:129], v[4:5] op_sel_hi:[0,1]
	v_pk_fma_f32 v[0:1], v[8:9], v[0:1], v[4:5]
	s_nop 0
	v_cvt_pk_f16_f32 v8, v0, v1
	v_pk_mul_f32 v[0:1], v[128:129], v[6:7] op_sel_hi:[0,1]
	v_pk_fma_f32 v[0:1], v[10:11], v[2:3], v[0:1]
	v_lshlrev_b32_e32 v10, 16, v108
	v_cvt_pk_f16_f32 v9, v0, v1
	ds_read_b128 v[0:3], v246 offset:480
	ds_read_b128 v[4:7], v247 offset:480
	v_and_b32_e32 v11, 0xffff0000, v108
	s_waitcnt lgkmcnt(0)
	v_pk_mul_f32 v[4:5], v[128:129], v[4:5] op_sel_hi:[0,1]
	v_pk_fma_f32 v[0:1], v[12:13], v[0:1], v[4:5]
	v_pk_mul_f32 v[4:5], v[128:129], v[6:7] op_sel_hi:[0,1]
	v_pk_fma_f32 v[2:3], v[14:15], v[2:3], v[4:5]
	v_cvt_pk_f16_f32 v0, v0, v1
	v_cvt_pk_f16_f32 v1, v2, v3
	v_add_u32_e32 v2, s0, v187
	v_ashrrev_i32_e32 v3, 31, v2
	v_lshl_add_u64 v[2:3], v[2:3], 2, s[58:59]
	ds_write2_b64 v214, v[8:9], v[0:1] offset0:28 offset1:30
	s_waitcnt lgkmcnt(0)
	s_barrier
	global_load_dword v8, v[2:3], off
	ds_read_b128 v[4:7], v215
	v_lshlrev_b32_e32 v12, 16, v124
	v_and_b32_e32 v13, 0xffff0000, v124
	v_lshlrev_b64 v[0:1], 12, v[166:167]
	v_lshl_add_u64 v[0:1], s[18:19], 0, v[0:1]
	s_waitcnt lgkmcnt(0)
	v_cvt_f32_f16_e32 v14, v4
	v_cvt_f32_f16_sdwa v15, v4 dst_sel:DWORD dst_unused:UNUSED_PAD src0_sel:WORD_1
	v_lshl_add_u64 v[0:1], v[0:1], 0, s[12:13]
	v_lshl_add_u64 v[0:1], v[0:1], 0, v[150:151]
	s_waitcnt vmcnt(0)
	v_pk_add_f32 v[14:15], v[8:9], v[14:15] op_sel_hi:[0,1]
	v_pk_mul_f32 v[10:11], v[14:15], v[10:11]
	v_cvt_f32_f16_e32 v14, v5
	v_cvt_f32_f16_sdwa v15, v5 dst_sel:DWORD dst_unused:UNUSED_PAD src0_sel:WORD_1
	v_pk_mul_f32 v[10:11], v[10:11], v[12:13]
	v_lshlrev_b32_e32 v12, 16, v125
	v_cvt_pk_bf16_f32 v4, v10, v11
	v_lshlrev_b32_e32 v10, 16, v109
	v_and_b32_e32 v11, 0xffff0000, v109
	v_pk_add_f32 v[14:15], v[8:9], v[14:15] op_sel_hi:[0,1]
	v_pk_mul_f32 v[10:11], v[14:15], v[10:11]
	v_cvt_f32_f16_e32 v14, v6
	v_cvt_f32_f16_sdwa v15, v6 dst_sel:DWORD dst_unused:UNUSED_PAD src0_sel:WORD_1
	v_and_b32_e32 v13, 0xffff0000, v125
	v_pk_mul_f32 v[10:11], v[10:11], v[12:13]
	v_lshlrev_b32_e32 v12, 16, v126
	v_cvt_pk_bf16_f32 v5, v10, v11
	v_lshlrev_b32_e32 v10, 16, v110
	v_and_b32_e32 v11, 0xffff0000, v110
	v_pk_add_f32 v[14:15], v[8:9], v[14:15] op_sel_hi:[0,1]
	v_pk_mul_f32 v[10:11], v[14:15], v[10:11]
	v_cvt_f32_f16_e32 v14, v7
	v_cvt_f32_f16_sdwa v15, v7 dst_sel:DWORD dst_unused:UNUSED_PAD src0_sel:WORD_1
	v_and_b32_e32 v13, 0xffff0000, v126
	v_pk_mul_f32 v[10:11], v[10:11], v[12:13]
	v_lshlrev_b32_e32 v12, 16, v127
	v_cvt_pk_bf16_f32 v6, v10, v11
	v_lshlrev_b32_e32 v10, 16, v111
	v_and_b32_e32 v11, 0xffff0000, v111
	v_pk_add_f32 v[8:9], v[8:9], v[14:15] op_sel_hi:[0,1]
	v_and_b32_e32 v13, 0xffff0000, v127
	v_pk_mul_f32 v[8:9], v[8:9], v[10:11]
	v_lshlrev_b32_e32 v10, 16, v100
	v_pk_mul_f32 v[8:9], v[8:9], v[12:13]
	v_and_b32_e32 v11, 0xffff0000, v100
	v_cvt_pk_bf16_f32 v7, v8, v9
	global_store_dwordx4 v[0:1], v[4:7], off
	global_load_dword v4, v[2:3], off offset:64
	ds_read_b128 v[6:9], v215 offset:8448
	v_lshlrev_b32_e32 v12, 16, v120
	v_and_b32_e32 v13, 0xffff0000, v120
	s_waitcnt lgkmcnt(0)
	v_cvt_f32_f16_e32 v14, v6
	v_cvt_f32_f16_sdwa v15, v6 dst_sel:DWORD dst_unused:UNUSED_PAD src0_sel:WORD_1
	s_waitcnt vmcnt(0)
	v_pk_add_f32 v[14:15], v[4:5], v[14:15] op_sel_hi:[0,1]
	v_pk_mul_f32 v[10:11], v[14:15], v[10:11]
	v_cvt_f32_f16_e32 v14, v7
	v_cvt_f32_f16_sdwa v15, v7 dst_sel:DWORD dst_unused:UNUSED_PAD src0_sel:WORD_1
	v_pk_mul_f32 v[10:11], v[10:11], v[12:13]
	v_lshlrev_b32_e32 v12, 16, v121
	v_cvt_pk_bf16_f32 v6, v10, v11
	v_lshlrev_b32_e32 v10, 16, v101
	v_and_b32_e32 v11, 0xffff0000, v101
	v_pk_add_f32 v[14:15], v[4:5], v[14:15] op_sel_hi:[0,1]
	v_pk_mul_f32 v[10:11], v[14:15], v[10:11]
	v_cvt_f32_f16_e32 v14, v8
	v_cvt_f32_f16_sdwa v15, v8 dst_sel:DWORD dst_unused:UNUSED_PAD src0_sel:WORD_1
	v_and_b32_e32 v13, 0xffff0000, v121
	v_pk_mul_f32 v[10:11], v[10:11], v[12:13]
	v_lshlrev_b32_e32 v12, 16, v122
	v_cvt_pk_bf16_f32 v7, v10, v11
	v_lshlrev_b32_e32 v10, 16, v102
	v_and_b32_e32 v11, 0xffff0000, v102
	v_pk_add_f32 v[14:15], v[4:5], v[14:15] op_sel_hi:[0,1]
	v_pk_mul_f32 v[10:11], v[14:15], v[10:11]
	v_cvt_f32_f16_e32 v14, v9
	v_cvt_f32_f16_sdwa v15, v9 dst_sel:DWORD dst_unused:UNUSED_PAD src0_sel:WORD_1
	v_and_b32_e32 v13, 0xffff0000, v122
	v_pk_mul_f32 v[10:11], v[10:11], v[12:13]
	v_lshlrev_b32_e32 v12, 16, v123
	v_cvt_pk_bf16_f32 v8, v10, v11
	v_lshlrev_b32_e32 v10, 16, v103
	v_and_b32_e32 v11, 0xffff0000, v103
	v_pk_add_f32 v[4:5], v[4:5], v[14:15] op_sel_hi:[0,1]
	v_and_b32_e32 v13, 0xffff0000, v123
	v_pk_mul_f32 v[4:5], v[4:5], v[10:11]
	v_lshlrev_b32_e32 v10, 16, v92
	v_pk_mul_f32 v[4:5], v[4:5], v[12:13]
	v_and_b32_e32 v11, 0xffff0000, v92
	v_cvt_pk_bf16_f32 v9, v4, v5
	v_add_co_u32_e32 v4, vcc, s3, v0
	v_lshlrev_b32_e32 v12, 16, v116
	s_nop 0
	v_addc_co_u32_e32 v5, vcc, 0, v1, vcc
	global_store_dwordx4 v[4:5], v[6:9], off
	global_load_dword v8, v[2:3], off offset:128
	ds_read_b128 v[4:7], v215 offset:16896
	v_and_b32_e32 v13, 0xffff0000, v116
	s_waitcnt lgkmcnt(0)
	v_cvt_f32_f16_e32 v14, v4
	v_cvt_f32_f16_sdwa v15, v4 dst_sel:DWORD dst_unused:UNUSED_PAD src0_sel:WORD_1
	s_waitcnt vmcnt(0)
	v_pk_add_f32 v[14:15], v[8:9], v[14:15] op_sel_hi:[0,1]
	v_pk_mul_f32 v[10:11], v[14:15], v[10:11]
	v_cvt_f32_f16_e32 v14, v5
	v_cvt_f32_f16_sdwa v15, v5 dst_sel:DWORD dst_unused:UNUSED_PAD src0_sel:WORD_1
	v_pk_mul_f32 v[10:11], v[10:11], v[12:13]
	v_lshlrev_b32_e32 v12, 16, v117
	v_cvt_pk_bf16_f32 v4, v10, v11
	v_lshlrev_b32_e32 v10, 16, v93
	v_and_b32_e32 v11, 0xffff0000, v93
	v_pk_add_f32 v[14:15], v[8:9], v[14:15] op_sel_hi:[0,1]
	v_pk_mul_f32 v[10:11], v[14:15], v[10:11]
	v_cvt_f32_f16_e32 v14, v6
	v_cvt_f32_f16_sdwa v15, v6 dst_sel:DWORD dst_unused:UNUSED_PAD src0_sel:WORD_1
	v_and_b32_e32 v13, 0xffff0000, v117
	v_pk_mul_f32 v[10:11], v[10:11], v[12:13]
	v_lshlrev_b32_e32 v12, 16, v118
	v_cvt_pk_bf16_f32 v5, v10, v11
	v_lshlrev_b32_e32 v10, 16, v94
	v_and_b32_e32 v11, 0xffff0000, v94
	v_pk_add_f32 v[14:15], v[8:9], v[14:15] op_sel_hi:[0,1]
	v_pk_mul_f32 v[10:11], v[14:15], v[10:11]
	v_cvt_f32_f16_e32 v14, v7
	v_cvt_f32_f16_sdwa v15, v7 dst_sel:DWORD dst_unused:UNUSED_PAD src0_sel:WORD_1
	v_and_b32_e32 v13, 0xffff0000, v118
	v_pk_mul_f32 v[10:11], v[10:11], v[12:13]
	v_lshlrev_b32_e32 v12, 16, v119
	v_cvt_pk_bf16_f32 v6, v10, v11
	v_lshlrev_b32_e32 v10, 16, v95
	v_and_b32_e32 v11, 0xffff0000, v95
	v_pk_add_f32 v[8:9], v[8:9], v[14:15] op_sel_hi:[0,1]
	v_and_b32_e32 v13, 0xffff0000, v119
	v_pk_mul_f32 v[8:9], v[8:9], v[10:11]
	v_lshlrev_b32_e32 v10, 16, v84
	v_pk_mul_f32 v[8:9], v[8:9], v[12:13]
	v_and_b32_e32 v11, 0xffff0000, v84
	v_cvt_pk_bf16_f32 v7, v8, v9
	v_add_co_u32_e32 v8, vcc, s87, v0
	v_lshlrev_b32_e32 v12, 16, v112
	s_nop 0
	v_addc_co_u32_e32 v9, vcc, 0, v1, vcc
	global_store_dwordx4 v[8:9], v[4:7], off
	global_load_dword v8, v[2:3], off offset:192
	ds_read_b128 v[4:7], v215 offset:25344
	v_and_b32_e32 v13, 0xffff0000, v112
	s_waitcnt lgkmcnt(0)
	v_cvt_f32_f16_e32 v14, v4
	v_cvt_f32_f16_sdwa v15, v4 dst_sel:DWORD dst_unused:UNUSED_PAD src0_sel:WORD_1
	s_waitcnt vmcnt(0)
	v_pk_add_f32 v[14:15], v[8:9], v[14:15] op_sel_hi:[0,1]
	v_pk_mul_f32 v[10:11], v[14:15], v[10:11]
	v_cvt_f32_f16_e32 v14, v5
	v_cvt_f32_f16_sdwa v15, v5 dst_sel:DWORD dst_unused:UNUSED_PAD src0_sel:WORD_1
	v_pk_mul_f32 v[10:11], v[10:11], v[12:13]
	v_lshlrev_b32_e32 v12, 16, v113
	v_cvt_pk_bf16_f32 v4, v10, v11
	v_lshlrev_b32_e32 v10, 16, v85
	v_and_b32_e32 v11, 0xffff0000, v85
	v_pk_add_f32 v[14:15], v[8:9], v[14:15] op_sel_hi:[0,1]
	v_pk_mul_f32 v[10:11], v[14:15], v[10:11]
	v_cvt_f32_f16_e32 v14, v6
	v_cvt_f32_f16_sdwa v15, v6 dst_sel:DWORD dst_unused:UNUSED_PAD src0_sel:WORD_1
	v_and_b32_e32 v13, 0xffff0000, v113
	v_pk_mul_f32 v[10:11], v[10:11], v[12:13]
	v_lshlrev_b32_e32 v12, 16, v114
	v_cvt_pk_bf16_f32 v5, v10, v11
	v_lshlrev_b32_e32 v10, 16, v86
	v_and_b32_e32 v11, 0xffff0000, v86
	v_pk_add_f32 v[14:15], v[8:9], v[14:15] op_sel_hi:[0,1]
	v_pk_mul_f32 v[10:11], v[14:15], v[10:11]
	v_cvt_f32_f16_e32 v14, v7
	v_cvt_f32_f16_sdwa v15, v7 dst_sel:DWORD dst_unused:UNUSED_PAD src0_sel:WORD_1
	v_and_b32_e32 v13, 0xffff0000, v114
	v_pk_mul_f32 v[10:11], v[10:11], v[12:13]
	v_lshlrev_b32_e32 v12, 16, v115
	v_cvt_pk_bf16_f32 v6, v10, v11
	v_lshlrev_b32_e32 v10, 16, v87
	v_and_b32_e32 v11, 0xffff0000, v87
	v_pk_add_f32 v[8:9], v[8:9], v[14:15] op_sel_hi:[0,1]
	v_and_b32_e32 v13, 0xffff0000, v115
	v_pk_mul_f32 v[8:9], v[8:9], v[10:11]
	v_lshlrev_b32_e32 v10, 16, v76
	v_pk_mul_f32 v[8:9], v[8:9], v[12:13]
	v_and_b32_e32 v11, 0xffff0000, v76
	v_cvt_pk_bf16_f32 v7, v8, v9
	v_add_co_u32_e32 v8, vcc, s88, v0
	v_lshlrev_b32_e32 v12, 16, v104
	s_nop 0
	v_addc_co_u32_e32 v9, vcc, 0, v1, vcc
	global_store_dwordx4 v[8:9], v[4:7], off
	global_load_dword v8, v[2:3], off offset:256
	ds_read_b128 v[4:7], v215 offset:33792
	v_and_b32_e32 v13, 0xffff0000, v104
	s_waitcnt lgkmcnt(0)
	v_cvt_f32_f16_e32 v14, v4
	v_cvt_f32_f16_sdwa v15, v4 dst_sel:DWORD dst_unused:UNUSED_PAD src0_sel:WORD_1
	s_waitcnt vmcnt(0)
	v_pk_add_f32 v[14:15], v[8:9], v[14:15] op_sel_hi:[0,1]
	v_pk_mul_f32 v[10:11], v[14:15], v[10:11]
	v_cvt_f32_f16_e32 v14, v5
	v_cvt_f32_f16_sdwa v15, v5 dst_sel:DWORD dst_unused:UNUSED_PAD src0_sel:WORD_1
	v_pk_mul_f32 v[10:11], v[10:11], v[12:13]
	v_lshlrev_b32_e32 v12, 16, v105
	v_cvt_pk_bf16_f32 v4, v10, v11
	v_lshlrev_b32_e32 v10, 16, v77
	v_and_b32_e32 v11, 0xffff0000, v77
	v_pk_add_f32 v[14:15], v[8:9], v[14:15] op_sel_hi:[0,1]
	v_pk_mul_f32 v[10:11], v[14:15], v[10:11]
	v_cvt_f32_f16_e32 v14, v6
	v_cvt_f32_f16_sdwa v15, v6 dst_sel:DWORD dst_unused:UNUSED_PAD src0_sel:WORD_1
	v_and_b32_e32 v13, 0xffff0000, v105
	v_pk_mul_f32 v[10:11], v[10:11], v[12:13]
	v_lshlrev_b32_e32 v12, 16, v106
	v_cvt_pk_bf16_f32 v5, v10, v11
	v_lshlrev_b32_e32 v10, 16, v78
	v_and_b32_e32 v11, 0xffff0000, v78
	v_pk_add_f32 v[14:15], v[8:9], v[14:15] op_sel_hi:[0,1]
	v_pk_mul_f32 v[10:11], v[14:15], v[10:11]
	v_cvt_f32_f16_e32 v14, v7
	v_cvt_f32_f16_sdwa v15, v7 dst_sel:DWORD dst_unused:UNUSED_PAD src0_sel:WORD_1
	v_and_b32_e32 v13, 0xffff0000, v106
	v_pk_mul_f32 v[10:11], v[10:11], v[12:13]
	v_lshlrev_b32_e32 v12, 16, v107
	v_cvt_pk_bf16_f32 v6, v10, v11
	v_lshlrev_b32_e32 v10, 16, v79
	v_and_b32_e32 v11, 0xffff0000, v79
	v_pk_add_f32 v[8:9], v[8:9], v[14:15] op_sel_hi:[0,1]
	v_and_b32_e32 v13, 0xffff0000, v107
	v_pk_mul_f32 v[8:9], v[8:9], v[10:11]
	v_lshlrev_b32_e32 v10, 16, v72
	v_pk_mul_f32 v[8:9], v[8:9], v[12:13]
	v_and_b32_e32 v11, 0xffff0000, v72
	v_cvt_pk_bf16_f32 v7, v8, v9
	v_add_co_u32_e32 v8, vcc, s89, v0
	v_lshlrev_b32_e32 v12, 16, v96
	s_nop 0
	v_addc_co_u32_e32 v9, vcc, 0, v1, vcc
	global_store_dwordx4 v[8:9], v[4:7], off
	global_load_dword v8, v[2:3], off offset:320
	ds_read_b128 v[4:7], v215 offset:42240
	v_and_b32_e32 v13, 0xffff0000, v96
	s_waitcnt lgkmcnt(0)
	v_cvt_f32_f16_e32 v14, v4
	v_cvt_f32_f16_sdwa v15, v4 dst_sel:DWORD dst_unused:UNUSED_PAD src0_sel:WORD_1
	s_waitcnt vmcnt(0)
	v_pk_add_f32 v[14:15], v[8:9], v[14:15] op_sel_hi:[0,1]
	v_pk_mul_f32 v[10:11], v[14:15], v[10:11]
	v_cvt_f32_f16_e32 v14, v5
	v_cvt_f32_f16_sdwa v15, v5 dst_sel:DWORD dst_unused:UNUSED_PAD src0_sel:WORD_1
	v_pk_mul_f32 v[10:11], v[10:11], v[12:13]
	v_lshlrev_b32_e32 v12, 16, v97
	v_cvt_pk_bf16_f32 v4, v10, v11
	v_lshlrev_b32_e32 v10, 16, v73
	v_and_b32_e32 v11, 0xffff0000, v73
	v_pk_add_f32 v[14:15], v[8:9], v[14:15] op_sel_hi:[0,1]
	v_pk_mul_f32 v[10:11], v[14:15], v[10:11]
	v_cvt_f32_f16_e32 v14, v6
	v_cvt_f32_f16_sdwa v15, v6 dst_sel:DWORD dst_unused:UNUSED_PAD src0_sel:WORD_1
	v_and_b32_e32 v13, 0xffff0000, v97
	v_pk_mul_f32 v[10:11], v[10:11], v[12:13]
	v_lshlrev_b32_e32 v12, 16, v98
	v_cvt_pk_bf16_f32 v5, v10, v11
	v_lshlrev_b32_e32 v10, 16, v74
	v_and_b32_e32 v11, 0xffff0000, v74
	v_pk_add_f32 v[14:15], v[8:9], v[14:15] op_sel_hi:[0,1]
	v_pk_mul_f32 v[10:11], v[14:15], v[10:11]
	v_cvt_f32_f16_e32 v14, v7
	v_cvt_f32_f16_sdwa v15, v7 dst_sel:DWORD dst_unused:UNUSED_PAD src0_sel:WORD_1
	v_and_b32_e32 v13, 0xffff0000, v98
	v_pk_mul_f32 v[10:11], v[10:11], v[12:13]
	v_lshlrev_b32_e32 v12, 16, v99
	v_cvt_pk_bf16_f32 v6, v10, v11
	v_lshlrev_b32_e32 v10, 16, v75
	v_and_b32_e32 v11, 0xffff0000, v75
	v_pk_add_f32 v[8:9], v[8:9], v[14:15] op_sel_hi:[0,1]
	v_and_b32_e32 v13, 0xffff0000, v99
	v_pk_mul_f32 v[8:9], v[8:9], v[10:11]
	v_lshlrev_b32_e32 v10, 16, v68
	v_pk_mul_f32 v[8:9], v[8:9], v[12:13]
	v_and_b32_e32 v11, 0xffff0000, v68
	v_cvt_pk_bf16_f32 v7, v8, v9
	v_add_co_u32_e32 v8, vcc, s73, v0
	v_lshlrev_b32_e32 v12, 16, v88
	s_nop 0
	v_addc_co_u32_e32 v9, vcc, 0, v1, vcc
	global_store_dwordx4 v[8:9], v[4:7], off
	global_load_dword v8, v[2:3], off offset:384
	ds_read_b128 v[4:7], v215 offset:50688
	v_and_b32_e32 v13, 0xffff0000, v88
	s_waitcnt lgkmcnt(0)
	v_cvt_f32_f16_e32 v14, v4
	v_cvt_f32_f16_sdwa v15, v4 dst_sel:DWORD dst_unused:UNUSED_PAD src0_sel:WORD_1
	s_waitcnt vmcnt(0)
	v_pk_add_f32 v[14:15], v[8:9], v[14:15] op_sel_hi:[0,1]
	v_pk_mul_f32 v[10:11], v[14:15], v[10:11]
	v_cvt_f32_f16_e32 v14, v5
	v_cvt_f32_f16_sdwa v15, v5 dst_sel:DWORD dst_unused:UNUSED_PAD src0_sel:WORD_1
	v_pk_mul_f32 v[10:11], v[10:11], v[12:13]
	v_lshlrev_b32_e32 v12, 16, v89
	v_cvt_pk_bf16_f32 v4, v10, v11
	v_lshlrev_b32_e32 v10, 16, v69
	v_and_b32_e32 v11, 0xffff0000, v69
	v_pk_add_f32 v[14:15], v[8:9], v[14:15] op_sel_hi:[0,1]
	v_pk_mul_f32 v[10:11], v[14:15], v[10:11]
	v_cvt_f32_f16_e32 v14, v6
	v_cvt_f32_f16_sdwa v15, v6 dst_sel:DWORD dst_unused:UNUSED_PAD src0_sel:WORD_1
	v_and_b32_e32 v13, 0xffff0000, v89
	v_pk_mul_f32 v[10:11], v[10:11], v[12:13]
	v_lshlrev_b32_e32 v12, 16, v90
	v_cvt_pk_bf16_f32 v5, v10, v11
	v_lshlrev_b32_e32 v10, 16, v70
	v_and_b32_e32 v11, 0xffff0000, v70
	v_pk_add_f32 v[14:15], v[8:9], v[14:15] op_sel_hi:[0,1]
	v_pk_mul_f32 v[10:11], v[14:15], v[10:11]
	v_cvt_f32_f16_e32 v14, v7
	v_cvt_f32_f16_sdwa v15, v7 dst_sel:DWORD dst_unused:UNUSED_PAD src0_sel:WORD_1
	v_and_b32_e32 v13, 0xffff0000, v90
	v_pk_mul_f32 v[10:11], v[10:11], v[12:13]
	v_lshlrev_b32_e32 v12, 16, v91
	v_cvt_pk_bf16_f32 v6, v10, v11
	v_lshlrev_b32_e32 v10, 16, v71
	v_and_b32_e32 v11, 0xffff0000, v71
	v_pk_add_f32 v[8:9], v[8:9], v[14:15] op_sel_hi:[0,1]
	v_and_b32_e32 v13, 0xffff0000, v91
	v_pk_mul_f32 v[8:9], v[8:9], v[10:11]
	v_lshlrev_b32_e32 v10, 16, v80
	v_pk_mul_f32 v[8:9], v[8:9], v[12:13]
	v_and_b32_e32 v11, 0xffff0000, v80
	v_cvt_pk_bf16_f32 v7, v8, v9
	v_add_co_u32_e32 v8, vcc, s90, v0
	s_nop 1
	v_addc_co_u32_e32 v9, vcc, 0, v1, vcc
	global_store_dwordx4 v[8:9], v[4:7], off
	global_load_dword v6, v[2:3], off offset:448
	ds_read_b128 v[2:5], v215 offset:59136
	v_lshlrev_b32_e32 v8, 16, v64
	v_and_b32_e32 v9, 0xffff0000, v64
	v_add_co_u32_e32 v0, vcc, 0x70000, v0
	s_waitcnt lgkmcnt(0)
	v_cvt_f32_f16_e32 v12, v2
	v_cvt_f32_f16_sdwa v13, v2 dst_sel:DWORD dst_unused:UNUSED_PAD src0_sel:WORD_1
	v_addc_co_u32_e32 v1, vcc, 0, v1, vcc
	s_waitcnt vmcnt(0)
	v_pk_add_f32 v[12:13], v[6:7], v[12:13] op_sel_hi:[0,1]
	v_pk_mul_f32 v[8:9], v[12:13], v[8:9]
	v_cvt_f32_f16_e32 v12, v3
	v_cvt_f32_f16_sdwa v13, v3 dst_sel:DWORD dst_unused:UNUSED_PAD src0_sel:WORD_1
	v_pk_mul_f32 v[8:9], v[8:9], v[10:11]
	v_lshlrev_b32_e32 v10, 16, v81
	v_cvt_pk_bf16_f32 v2, v8, v9
	v_lshlrev_b32_e32 v8, 16, v65
	v_and_b32_e32 v9, 0xffff0000, v65
	v_pk_add_f32 v[12:13], v[6:7], v[12:13] op_sel_hi:[0,1]
	v_pk_mul_f32 v[8:9], v[12:13], v[8:9]
	v_cvt_f32_f16_e32 v12, v4
	v_cvt_f32_f16_sdwa v13, v4 dst_sel:DWORD dst_unused:UNUSED_PAD src0_sel:WORD_1
	v_and_b32_e32 v11, 0xffff0000, v81
	v_pk_mul_f32 v[8:9], v[8:9], v[10:11]
	v_lshlrev_b32_e32 v10, 16, v82
	v_cvt_pk_bf16_f32 v3, v8, v9
	v_lshlrev_b32_e32 v8, 16, v66
	v_and_b32_e32 v9, 0xffff0000, v66
	v_pk_add_f32 v[12:13], v[6:7], v[12:13] op_sel_hi:[0,1]
	v_pk_mul_f32 v[8:9], v[12:13], v[8:9]
	v_cvt_f32_f16_e32 v12, v5
	v_cvt_f32_f16_sdwa v13, v5 dst_sel:DWORD dst_unused:UNUSED_PAD src0_sel:WORD_1
	v_and_b32_e32 v11, 0xffff0000, v82
	v_pk_mul_f32 v[8:9], v[8:9], v[10:11]
	v_lshlrev_b32_e32 v10, 16, v83
	v_cvt_pk_bf16_f32 v4, v8, v9
	v_lshlrev_b32_e32 v8, 16, v67
	v_and_b32_e32 v9, 0xffff0000, v67
	v_pk_add_f32 v[6:7], v[6:7], v[12:13] op_sel_hi:[0,1]
	v_and_b32_e32 v11, 0xffff0000, v83
	v_pk_mul_f32 v[6:7], v[6:7], v[8:9]
	s_nop 0
	v_pk_mul_f32 v[6:7], v[6:7], v[10:11]
	s_nop 0
	v_cvt_pk_bf16_f32 v5, v6, v7
	global_store_dwordx4 v[0:1], v[2:5], off
